# in-proj: first K-iteration peeled with SrcC=0 (no accumulator zeroing v_movs)
# speedup vs baseline: 1.0254x; 1.0055x over previous
; #define PG8_STAGE(bufoff, gbase, voff) do { _Pragma("unroll") for (int _i = 0; _i < 2; ++_i) \
;         __builtin_amdgcn_global_load_lds((const unsigned*)((const char*)(gbase) + (voff)[_i]), (LAS unsigned*)(lds + (bufoff) + ldsw + _i * 8192), 16, 0, 0); } while (0)
; #define PG8_LDA(dst, b, h) do { _Pragma("unroll") for (int m = 0; m < 4; ++m) _Pragma("unroll") for (int k = 0; k < 2; ++k) dst[m][k] = *(const LAS bf16x8*)(lds + PG8_SA(b, h) + aoff + m * 2048 + k * 1024); } while (0)
; #define PG8_LDB(dst, b, h) do { _Pragma("unroll") for (int n = 0; n < 2; ++n) _Pragma("unroll") for (int k = 0; k < 2; ++k) dst[n][k] = *(const LAS bf16x8*)(lds + PG8_SB(b, h) + boff + n * 2048 + k * 1024); } while (0)
; #define PG8_MMA(ai, bj, At, Bt) do { __builtin_amdgcn_s_setprio(1); _Pragma("unroll") for (int m = 0; m < 4; ++m) _Pragma("unroll") for (int n = 0; n < 2; ++n) _Pragma("unroll") for (int k = 0; k < 2; ++k) \
;         acc[ai][bj][m][n] = __builtin_amdgcn_mfma_f32_16x16x32_bf16(Bt[n][k], At[m][k], acc[ai][bj][m][n], 0, 0, 0); __builtin_amdgcn_s_setprio(0); } while (0)
; #define PG8_WAIT_V(n) asm volatile("s_waitcnt vmcnt(" #n ")" ::: "memory")
; #define PG8_WAIT_L(n) asm volatile("s_waitcnt lgkmcnt(" #n ")" ::: "memory")
; #define PG8_BAR __builtin_amdgcn_s_barrier()
; #define PG8_SCHED __builtin_amdgcn_sched_barrier(0)
; template <class Prog>
; __device__ __forceinline__ void gemm_phase(LAS unsigned char* lds, const int K, const Prog& S) {
;     ...
;     f32x4 acc[2][2][4][2];
; #pragma unroll
;     for (int a = 0; a < 2; ++a)
; #pragma unroll
;         for (int b = 0; b < 2; ++b)
; #pragma unroll
;             for (int m = 0; m < 4; ++m)
; #pragma unroll
;                 for (int n = 0; n < 2; ++n) acc[a][b][m][n] = (f32x4){0.f, 0.f, 0.f, 0.f};
;     ...
;             PG8_LDB(B0, 0, 0); PG8_SCHED; PG8_LDA(At, 0, 0); PG8_STAGE(PG8_SA(1, 1), a1 + hstep, voffA);
;             PG8_WAIT_L(8); PG8_BAR; PG8_WAIT_L(0); PG8_MMA(0, 0, At, B0); PG8_BAR; PG8_SCHED;
;             PG8_LDB(B1, 0, 1); PG8_STAGE(PG8_SB(0, 0), b2, voffB);
;             PG8_BAR; PG8_WAIT_L(0); PG8_MMA(0, 1, At, B1); PG8_BAR;
;             PG8_LDA(At, 0, 1); PG8_STAGE(PG8_SA(0, 0), a2, voffA);
;             PG8_BAR; PG8_WAIT_L(0); PG8_MMA(1, 0, At, B0); PG8_BAR; PG8_SCHED;
;             PG8_STAGE(PG8_SB(0, 1), b2 + hstep, voffB);
;             PG8_WAIT_V(6); PG8_BAR; PG8_MMA(1, 1, At, B1); PG8_BAR;
.LBB0_100:
	s_add_u32 s40, s40, 0x80080
	s_addc_u32 s41, s41, 0
	s_add_u32 s9, s44, 0x100
	s_addc_u32 s15, s45, 0
	s_mov_b32 s69, -2
	s_waitcnt vmcnt(16)
	v_add_u32_e32 v244, 0x10000, v205
	s_add_u32 s44, s40, 0xfff80080
	s_addc_u32 s45, s41, -1
	s_cmp_eq_u32 s69, 28
	s_cselect_b32 s47, s5, s45
	s_cselect_b32 s46, s4, s44
	s_cselect_b32 s45, s13, s15
	s_cselect_b32 s44, s12, s9
	s_add_u32 s76, s40, 0xfff80000
	s_addc_u32 s77, s41, -1
	ds_read_b128 v[128:131], v244
	ds_read_b128 v[132:135], v244 offset:1024
	ds_read_b128 v[136:139], v244 offset:2048
	ds_read_b128 v[140:143], v244 offset:3072
	s_add_i32 m0, s92, 0x8000
	ds_read_b128 v[188:191], v244 offset:16384
	ds_read_b128 v[196:199], v244 offset:17408
	ds_read_b128 v[200:203], v244 offset:18432
	ds_read_b128 v[218:221], v244 offset:19456
	global_load_lds_dwordx4 v184, s[76:77]
	s_add_i32 m0, s92, 0xa000
	ds_read_b128 v[144:147], v216
	ds_read_b128 v[148:151], v216 offset:1024
	ds_read_b128 v[152:155], v216 offset:2048
	ds_read_b128 v[156:159], v216 offset:3072
	global_load_lds_dwordx4 v186, s[76:77]
	s_add_i32 m0, s92, 0xc000
	ds_read_b128 v[160:163], v216 offset:4096
	ds_read_b128 v[164:167], v216 offset:5120
	ds_read_b128 v[168:171], v216 offset:6144
	ds_read_b128 v[172:175], v216 offset:7168
	global_load_lds_dwordx4 v184, s[40:41]
	s_add_i32 m0, s92, 0xe000
	s_nop 0
	global_load_lds_dwordx4 v186, s[40:41]
	s_waitcnt lgkmcnt(0)
	s_barrier
	v_mfma_f32_16x16x32_bf16 v[124:127], v[128:131], v[144:147], 0
	v_mfma_f32_16x16x32_bf16 v[116:119], v[136:139], v[144:147], 0
	v_mfma_f32_16x16x32_bf16 v[108:111], v[128:131], v[152:155], 0
	v_mfma_f32_16x16x32_bf16 v[100:103], v[136:139], v[152:155], 0
	v_mfma_f32_16x16x32_bf16 v[92:95], v[128:131], v[160:163], 0
	v_mfma_f32_16x16x32_bf16 v[84:87], v[136:139], v[160:163], 0
	v_mfma_f32_16x16x32_bf16 v[76:79], v[128:131], v[168:171], 0
	v_mfma_f32_16x16x32_bf16 v[68:71], v[136:139], v[168:171], 0
	v_mfma_f32_16x16x32_bf16 v[124:127], v[132:135], v[148:151], v[124:127]
	v_mfma_f32_16x16x32_bf16 v[116:119], v[140:143], v[148:151], v[116:119]
	v_mfma_f32_16x16x32_bf16 v[108:111], v[132:135], v[156:159], v[108:111]
	v_mfma_f32_16x16x32_bf16 v[100:103], v[140:143], v[156:159], v[100:103]
	v_mfma_f32_16x16x32_bf16 v[92:95], v[132:135], v[164:167], v[92:95]
	v_mfma_f32_16x16x32_bf16 v[84:87], v[140:143], v[164:167], v[84:87]
	v_mfma_f32_16x16x32_bf16 v[76:79], v[132:135], v[172:175], v[76:79]
	v_mfma_f32_16x16x32_bf16 v[68:71], v[140:143], v[172:175], v[68:71]
	v_mfma_f32_16x16x32_bf16 v[120:123], v[188:191], v[144:147], 0
	v_mfma_f32_16x16x32_bf16 v[112:115], v[200:203], v[144:147], 0
	v_mfma_f32_16x16x32_bf16 v[104:107], v[188:191], v[152:155], 0
	v_mfma_f32_16x16x32_bf16 v[96:99], v[200:203], v[152:155], 0
	v_mfma_f32_16x16x32_bf16 v[88:91], v[188:191], v[160:163], 0
	v_mfma_f32_16x16x32_bf16 v[80:83], v[200:203], v[160:163], 0
	v_mfma_f32_16x16x32_bf16 v[72:75], v[188:191], v[168:171], 0
	v_mfma_f32_16x16x32_bf16 v[64:67], v[200:203], v[168:171], 0
	v_mfma_f32_16x16x32_bf16 v[120:123], v[196:199], v[148:151], v[120:123]
	v_mfma_f32_16x16x32_bf16 v[112:115], v[218:221], v[148:151], v[112:115]
	v_mfma_f32_16x16x32_bf16 v[104:107], v[196:199], v[156:159], v[104:107]
	v_mfma_f32_16x16x32_bf16 v[96:99], v[218:221], v[156:159], v[96:99]
	v_mfma_f32_16x16x32_bf16 v[88:91], v[196:199], v[164:167], v[88:91]
	v_mfma_f32_16x16x32_bf16 v[80:83], v[218:221], v[164:167], v[80:83]
	v_mfma_f32_16x16x32_bf16 v[72:75], v[196:199], v[172:175], v[72:75]
	v_mfma_f32_16x16x32_bf16 v[64:67], v[218:221], v[172:175], v[64:67]
	s_barrier
	ds_read_b128 v[144:147], v216 offset:16384
	ds_read_b128 v[148:151], v216 offset:17408
	ds_read_b128 v[152:155], v216 offset:18432
	ds_read_b128 v[156:159], v216 offset:19456
	s_add_i32 m0, s92, 0x10000
	ds_read_b128 v[160:163], v216 offset:20480
	ds_read_b128 v[164:167], v216 offset:21504
	ds_read_b128 v[168:171], v216 offset:22528
	ds_read_b128 v[172:175], v216 offset:23552
	global_load_lds_dwordx4 v192, s[44:45]
	s_add_i32 m0, s92, 0x12000
	s_nop 0
	global_load_lds_dwordx4 v180, s[44:45]
	s_add_u32 s76, s44, 0x80000
	s_addc_u32 s77, s45, 0
	s_add_i32 m0, s92, 0x14000
	s_nop 0
	global_load_lds_dwordx4 v192, s[76:77]
	s_add_i32 m0, s92, 0x16000
	s_nop 0
	global_load_lds_dwordx4 v180, s[76:77]
	s_waitcnt vmcnt(4)
	s_waitcnt lgkmcnt(0)
	s_barrier
	v_mfma_f32_16x16x32_bf16 v[60:63], v[128:131], v[144:147], 0
	v_mfma_f32_16x16x32_bf16 v[52:55], v[136:139], v[144:147], 0
	v_mfma_f32_16x16x32_bf16 v[44:47], v[128:131], v[152:155], 0
	v_mfma_f32_16x16x32_bf16 v[36:39], v[136:139], v[152:155], 0
	v_mfma_f32_16x16x32_bf16 v[28:31], v[128:131], v[160:163], 0
	v_mfma_f32_16x16x32_bf16 v[20:23], v[136:139], v[160:163], 0
	v_mfma_f32_16x16x32_bf16 v[12:15], v[128:131], v[168:171], 0
	v_mfma_f32_16x16x32_bf16 v[4:7], v[136:139], v[168:171], 0
	v_mfma_f32_16x16x32_bf16 v[60:63], v[132:135], v[148:151], v[60:63]
	v_mfma_f32_16x16x32_bf16 v[52:55], v[140:143], v[148:151], v[52:55]
	v_mfma_f32_16x16x32_bf16 v[44:47], v[132:135], v[156:159], v[44:47]
	v_mfma_f32_16x16x32_bf16 v[36:39], v[140:143], v[156:159], v[36:39]
	v_mfma_f32_16x16x32_bf16 v[28:31], v[132:135], v[164:167], v[28:31]
	v_mfma_f32_16x16x32_bf16 v[20:23], v[140:143], v[164:167], v[20:23]
	v_mfma_f32_16x16x32_bf16 v[12:15], v[132:135], v[172:175], v[12:15]
	v_mfma_f32_16x16x32_bf16 v[4:7], v[140:143], v[172:175], v[4:7]
	v_mfma_f32_16x16x32_bf16 v[56:59], v[188:191], v[144:147], 0
	v_mfma_f32_16x16x32_bf16 v[48:51], v[200:203], v[144:147], 0
	v_mfma_f32_16x16x32_bf16 v[40:43], v[188:191], v[152:155], 0
	v_mfma_f32_16x16x32_bf16 v[32:35], v[200:203], v[152:155], 0
	v_mfma_f32_16x16x32_bf16 v[24:27], v[188:191], v[160:163], 0
	v_mfma_f32_16x16x32_bf16 v[16:19], v[200:203], v[160:163], 0
	v_mfma_f32_16x16x32_bf16 v[8:11], v[188:191], v[168:171], 0
	v_mfma_f32_16x16x32_bf16 v[0:3], v[200:203], v[168:171], 0
	v_mfma_f32_16x16x32_bf16 v[56:59], v[196:199], v[148:151], v[56:59]
	v_mfma_f32_16x16x32_bf16 v[48:51], v[218:221], v[148:151], v[48:51]
	v_mfma_f32_16x16x32_bf16 v[40:43], v[196:199], v[156:159], v[40:43]
	v_mfma_f32_16x16x32_bf16 v[32:35], v[218:221], v[156:159], v[32:35]
	v_mfma_f32_16x16x32_bf16 v[24:27], v[196:199], v[164:167], v[24:27]
	v_mfma_f32_16x16x32_bf16 v[16:19], v[218:221], v[164:167], v[16:19]
	v_mfma_f32_16x16x32_bf16 v[8:11], v[196:199], v[172:175], v[8:11]
	v_mfma_f32_16x16x32_bf16 v[0:3], v[218:221], v[172:175], v[0:3]
	s_barrier
; #define PG8_STAGE(bufoff, gbase, voff) do { _Pragma("unroll") for (int _i = 0; _i < 2; ++_i) \
;         __builtin_amdgcn_global_load_lds((const unsigned*)((const char*)(gbase) + (voff)[_i]), (LAS unsigned*)(lds + (bufoff) + ldsw + _i * 8192), 16, 0, 0); } while (0)
; #define PG8_LDA(dst, b, h) do { _Pragma("unroll") for (int m = 0; m < 4; ++m) _Pragma("unroll") for (int k = 0; k < 2; ++k) dst[m][k] = *(const LAS bf16x8*)(lds + PG8_SA(b, h) + aoff + m * 2048 + k * 1024); } while (0)
; #define PG8_LDB(dst, b, h) do { _Pragma("unroll") for (int n = 0; n < 2; ++n) _Pragma("unroll") for (int k = 0; k < 2; ++k) dst[n][k] = *(const LAS bf16x8*)(lds + PG8_SB(b, h) + boff + n * 2048 + k * 1024); } while (0)
; #define PG8_MMA(ai, bj, At, Bt) do { __builtin_amdgcn_s_setprio(1); _Pragma("unroll") for (int m = 0; m < 4; ++m) _Pragma("unroll") for (int n = 0; n < 2; ++n) _Pragma("unroll") for (int k = 0; k < 2; ++k) \
;         acc[ai][bj][m][n] = __builtin_amdgcn_mfma_f32_16x16x32_bf16(Bt[n][k], At[m][k], acc[ai][bj][m][n], 0, 0, 0); __builtin_amdgcn_s_setprio(0); } while (0)
; #define PG8_WAIT_V(n) asm volatile("s_waitcnt vmcnt(" #n ")" ::: "memory")
; #define PG8_WAIT_L(n) asm volatile("s_waitcnt lgkmcnt(" #n ")" ::: "memory")
; #define PG8_BAR __builtin_amdgcn_s_barrier()
; #define PG8_SCHED __builtin_amdgcn_sched_barrier(0)
; template <class Prog>
; __device__ __forceinline__ void gemm_phase(LAS unsigned char* lds, const int K, const Prog& S) {
;     ...
;             PG8_LDB(B0, 1, 0); PG8_SCHED; PG8_LDA(At, 1, 0); PG8_STAGE(PG8_SA(0, 1), a2 + hstep, voffA);
;             PG8_WAIT_L(8); PG8_BAR; PG8_WAIT_L(0); PG8_MMA(0, 0, At, B0); PG8_BAR; PG8_SCHED;
;             PG8_LDB(B1, 1, 1); PG8_STAGE(PG8_SB(1, 0), b3, voffB);
;             PG8_BAR; PG8_WAIT_L(0); PG8_MMA(0, 1, At, B1); PG8_BAR;
;             PG8_LDA(At, 1, 1); PG8_STAGE(PG8_SA(1, 0), a3, voffA);
;             PG8_BAR; PG8_WAIT_L(0); PG8_MMA(1, 0, At, B0); PG8_BAR; PG8_SCHED;
;             PG8_STAGE(PG8_SB(1, 1), b3 + hstep, voffB);
;             PG8_WAIT_V(6); PG8_BAR; PG8_MMA(1, 1, At, B1); PG8_BAR;
	s_add_u32 s76, s46, 0x80000
	s_addc_u32 s77, s47, 0
	ds_read_b128 v[128:131], v244 offset:32768
	ds_read_b128 v[132:135], v244 offset:33792
	ds_read_b128 v[136:139], v244 offset:34816
	ds_read_b128 v[140:143], v244 offset:35840
	s_mov_b32 m0, s92
	ds_read_b128 v[188:191], v244 offset:49152
	ds_read_b128 v[196:199], v244 offset:50176
	ds_read_b128 v[200:203], v244 offset:51200
	ds_read_b128 v[218:221], v244 offset:52224
	global_load_lds_dwordx4 v176, s[46:47]
	s_add_i32 m0, s92, 0x2000
	ds_read_b128 v[144:147], v216 offset:32768
	ds_read_b128 v[148:151], v216 offset:33792
	ds_read_b128 v[152:155], v216 offset:34816
	ds_read_b128 v[156:159], v216 offset:35840
	global_load_lds_dwordx4 v178, s[46:47]
	s_add_i32 m0, s92, 0x4000
	ds_read_b128 v[160:163], v216 offset:36864
	ds_read_b128 v[164:167], v216 offset:37888
	ds_read_b128 v[168:171], v216 offset:38912
	ds_read_b128 v[172:175], v216 offset:39936
	global_load_lds_dwordx4 v176, s[76:77]
	s_add_i32 m0, s92, 0x6000
	s_nop 0
	global_load_lds_dwordx4 v178, s[76:77]
	s_waitcnt lgkmcnt(0)
	s_barrier
	v_mfma_f32_16x16x32_bf16 v[124:127], v[128:131], v[144:147], v[124:127]
	v_mfma_f32_16x16x32_bf16 v[116:119], v[136:139], v[144:147], v[116:119]
	v_mfma_f32_16x16x32_bf16 v[108:111], v[128:131], v[152:155], v[108:111]
	v_mfma_f32_16x16x32_bf16 v[100:103], v[136:139], v[152:155], v[100:103]
	v_mfma_f32_16x16x32_bf16 v[92:95], v[128:131], v[160:163], v[92:95]
	v_mfma_f32_16x16x32_bf16 v[84:87], v[136:139], v[160:163], v[84:87]
	v_mfma_f32_16x16x32_bf16 v[76:79], v[128:131], v[168:171], v[76:79]
	v_mfma_f32_16x16x32_bf16 v[68:71], v[136:139], v[168:171], v[68:71]
	v_mfma_f32_16x16x32_bf16 v[124:127], v[132:135], v[148:151], v[124:127]
	v_mfma_f32_16x16x32_bf16 v[116:119], v[140:143], v[148:151], v[116:119]
	v_mfma_f32_16x16x32_bf16 v[108:111], v[132:135], v[156:159], v[108:111]
	v_mfma_f32_16x16x32_bf16 v[100:103], v[140:143], v[156:159], v[100:103]
	v_mfma_f32_16x16x32_bf16 v[92:95], v[132:135], v[164:167], v[92:95]
	v_mfma_f32_16x16x32_bf16 v[84:87], v[140:143], v[164:167], v[84:87]
	v_mfma_f32_16x16x32_bf16 v[76:79], v[132:135], v[172:175], v[76:79]
	v_mfma_f32_16x16x32_bf16 v[68:71], v[140:143], v[172:175], v[68:71]
	v_mfma_f32_16x16x32_bf16 v[120:123], v[188:191], v[144:147], v[120:123]
	v_mfma_f32_16x16x32_bf16 v[112:115], v[200:203], v[144:147], v[112:115]
	v_mfma_f32_16x16x32_bf16 v[104:107], v[188:191], v[152:155], v[104:107]
	v_mfma_f32_16x16x32_bf16 v[96:99], v[200:203], v[152:155], v[96:99]
	v_mfma_f32_16x16x32_bf16 v[88:91], v[188:191], v[160:163], v[88:91]
	v_mfma_f32_16x16x32_bf16 v[80:83], v[200:203], v[160:163], v[80:83]
	v_mfma_f32_16x16x32_bf16 v[72:75], v[188:191], v[168:171], v[72:75]
	v_mfma_f32_16x16x32_bf16 v[64:67], v[200:203], v[168:171], v[64:67]
	v_mfma_f32_16x16x32_bf16 v[120:123], v[196:199], v[148:151], v[120:123]
	v_mfma_f32_16x16x32_bf16 v[112:115], v[218:221], v[148:151], v[112:115]
	v_mfma_f32_16x16x32_bf16 v[104:107], v[196:199], v[156:159], v[104:107]
	v_mfma_f32_16x16x32_bf16 v[96:99], v[218:221], v[156:159], v[96:99]
	v_mfma_f32_16x16x32_bf16 v[88:91], v[196:199], v[164:167], v[88:91]
	v_mfma_f32_16x16x32_bf16 v[80:83], v[218:221], v[164:167], v[80:83]
	v_mfma_f32_16x16x32_bf16 v[72:75], v[196:199], v[172:175], v[72:75]
	v_mfma_f32_16x16x32_bf16 v[64:67], v[218:221], v[172:175], v[64:67]
	s_barrier
	s_add_u32 s76, s44, 0x80
	s_addc_u32 s77, s45, 0
	ds_read_b128 v[144:147], v216 offset:49152
	ds_read_b128 v[148:151], v216 offset:50176
	ds_read_b128 v[152:155], v216 offset:51200
	ds_read_b128 v[156:159], v216 offset:52224
	s_add_i32 m0, s92, 0x18000
	ds_read_b128 v[160:163], v216 offset:53248
	ds_read_b128 v[164:167], v216 offset:54272
	ds_read_b128 v[168:171], v216 offset:55296
	ds_read_b128 v[172:175], v216 offset:56320
	global_load_lds_dwordx4 v192, s[76:77]
	s_add_i32 m0, s92, 0x1a000
	s_nop 0
	global_load_lds_dwordx4 v180, s[76:77]
	s_add_u32 s76, s44, 0x80080
	s_addc_u32 s77, s45, 0
	s_add_i32 m0, s92, 0x1c000
	s_nop 0
	global_load_lds_dwordx4 v192, s[76:77]
	s_add_i32 m0, s92, 0x1e000
	s_nop 0
	global_load_lds_dwordx4 v180, s[76:77]
	s_waitcnt vmcnt(4)
	s_waitcnt lgkmcnt(0)
	s_barrier
	v_mfma_f32_16x16x32_bf16 v[60:63], v[128:131], v[144:147], v[60:63]
	v_mfma_f32_16x16x32_bf16 v[52:55], v[136:139], v[144:147], v[52:55]
	v_mfma_f32_16x16x32_bf16 v[44:47], v[128:131], v[152:155], v[44:47]
	v_mfma_f32_16x16x32_bf16 v[36:39], v[136:139], v[152:155], v[36:39]
	v_mfma_f32_16x16x32_bf16 v[28:31], v[128:131], v[160:163], v[28:31]
	v_mfma_f32_16x16x32_bf16 v[20:23], v[136:139], v[160:163], v[20:23]
	v_mfma_f32_16x16x32_bf16 v[12:15], v[128:131], v[168:171], v[12:15]
	v_mfma_f32_16x16x32_bf16 v[4:7], v[136:139], v[168:171], v[4:7]
	v_mfma_f32_16x16x32_bf16 v[60:63], v[132:135], v[148:151], v[60:63]
	v_mfma_f32_16x16x32_bf16 v[52:55], v[140:143], v[148:151], v[52:55]
	v_mfma_f32_16x16x32_bf16 v[44:47], v[132:135], v[156:159], v[44:47]
	v_mfma_f32_16x16x32_bf16 v[36:39], v[140:143], v[156:159], v[36:39]
	v_mfma_f32_16x16x32_bf16 v[28:31], v[132:135], v[164:167], v[28:31]
	v_mfma_f32_16x16x32_bf16 v[20:23], v[140:143], v[164:167], v[20:23]
	v_mfma_f32_16x16x32_bf16 v[12:15], v[132:135], v[172:175], v[12:15]
	v_mfma_f32_16x16x32_bf16 v[4:7], v[140:143], v[172:175], v[4:7]
	v_mfma_f32_16x16x32_bf16 v[56:59], v[188:191], v[144:147], v[56:59]
	v_mfma_f32_16x16x32_bf16 v[48:51], v[200:203], v[144:147], v[48:51]
	v_mfma_f32_16x16x32_bf16 v[40:43], v[188:191], v[152:155], v[40:43]
	v_mfma_f32_16x16x32_bf16 v[32:35], v[200:203], v[152:155], v[32:35]
	v_mfma_f32_16x16x32_bf16 v[24:27], v[188:191], v[160:163], v[24:27]
	v_mfma_f32_16x16x32_bf16 v[16:19], v[200:203], v[160:163], v[16:19]
	v_mfma_f32_16x16x32_bf16 v[8:11], v[188:191], v[168:171], v[8:11]
	v_mfma_f32_16x16x32_bf16 v[0:3], v[200:203], v[168:171], v[0:3]
	v_mfma_f32_16x16x32_bf16 v[56:59], v[196:199], v[148:151], v[56:59]
	v_mfma_f32_16x16x32_bf16 v[48:51], v[218:221], v[148:151], v[48:51]
	v_mfma_f32_16x16x32_bf16 v[40:43], v[196:199], v[156:159], v[40:43]
	v_mfma_f32_16x16x32_bf16 v[32:35], v[218:221], v[156:159], v[32:35]
	v_mfma_f32_16x16x32_bf16 v[24:27], v[196:199], v[164:167], v[24:27]
	v_mfma_f32_16x16x32_bf16 v[16:19], v[218:221], v[164:167], v[16:19]
	v_mfma_f32_16x16x32_bf16 v[8:11], v[196:199], v[172:175], v[8:11]
	v_mfma_f32_16x16x32_bf16 v[0:3], v[218:221], v[172:175], v[0:3]
	s_add_i32 s69, s69, 2
	s_add_u32 s40, s40, 0x100
	s_addc_u32 s41, s41, 0
	s_add_u32 s9, s9, 0x100
	s_addc_u32 s15, s15, 0
	s_cmp_gt_u32 s69, 29
	s_barrier
	.p2align 6
